# pair barrier pollers sleep 12 (768 cycles) between polls instead of 1, to keep 248 pollers from interfering with the leaders' L2 write-back
# speedup vs baseline: 1.0156x; 1.0156x over previous
.Lgb_pair_244:
	global_load_dword v3, v2, s[12:13] sc1
	s_waitcnt vmcnt(0)
	v_readfirstlane_b32 s4, v3
	s_nop 3
	s_cmp_ge_u32 s4, s16
	s_cbranch_scc1 .Lgb_pair_ok_244
	s_sleep 12
	s_add_i32 s1, s1, 1
	s_cmp_lt_u32 s1, 0x40000
	s_cbranch_scc1 .Lgb_pair_244
